# FFN-up conv+SiLU epilogue: mask-free row loop now also for the last strip (halo-row stores predicated), so no wave falls back to the slow path
# speedup vs baseline: 1.0340x; 1.0086x over previous
.LBB0_640:
	s_and_b64 s[2:3], s[8:9], exec
	s_waitcnt vmcnt(0)
	v_readlane_b32 s2, v255, 15
	v_readlane_b32 s4, v255, 19
	v_readlane_b32 s3, v255, 16
	v_readlane_b32 s5, v255, 20
	s_cselect_b32 s42, s2, s4
	v_readlane_b32 s2, v255, 17
	s_cselect_b32 s28, s51, 0
	s_cselect_b32 s29, s52, 0
	s_cselect_b32 s43, s3, s5
	s_cselect_b32 s46, s2, 0
	s_cmp_lt_i32 s44, 4
	s_mov_b64 s[2:3], -1
	s_waitcnt vmcnt(0) lgkmcnt(0)
	s_barrier
	s_cbranch_scc1 .LBB0_1047
	s_cmp_lt_i32 s44, 6
	s_cbranch_scc1 .LBB0_1041
	s_cmp_gt_i32 s44, 6
	s_cbranch_scc0 .LBB0_654
	s_movk_i32 s15, 0x210
	v_lshlrev_b32_e32 v0, 3, v223
	v_mul_lo_u32 v132, v225, s15
	v_cvt_pk_bf16_f32 v131, v128, v129
	v_cvt_pk_bf16_f32 v130, v126, v127
	v_add3_u32 v0, v224, v132, v0
	v_cvt_pk_bf16_f32 v133, v124, v125
	v_cvt_pk_bf16_f32 v132, v122, v123
	ds_write2_b64 v0, v[130:131], v[132:133] offset1:4
	v_cvt_pk_bf16_f32 v131, v120, v121
	v_cvt_pk_bf16_f32 v130, v118, v119
	v_cvt_pk_bf16_f32 v133, v116, v117
	v_cvt_pk_bf16_f32 v132, v114, v115
	ds_write2_b64 v0, v[130:131], v[132:133] offset0:32 offset1:36
	v_cvt_pk_bf16_f32 v131, v112, v113
	v_cvt_pk_bf16_f32 v130, v110, v111
	v_cvt_pk_bf16_f32 v133, v108, v109
	v_cvt_pk_bf16_f32 v132, v106, v107
	v_add_u32_e32 v134, 0x2000, v0
	ds_write2_b64 v134, v[130:131], v[132:133] offset0:32 offset1:36
	v_cvt_pk_bf16_f32 v131, v104, v105
	v_cvt_pk_bf16_f32 v130, v102, v103
	v_cvt_pk_bf16_f32 v133, v100, v101
	v_cvt_pk_bf16_f32 v132, v98, v99
	ds_write2_b64 v134, v[130:131], v[132:133] offset0:64 offset1:68
	v_cvt_pk_bf16_f32 v131, v96, v97
	v_cvt_pk_bf16_f32 v130, v94, v95
	v_cvt_pk_bf16_f32 v133, v92, v93
	v_cvt_pk_bf16_f32 v132, v90, v91
	v_add_u32_e32 v134, 0x4000, v0
	ds_write2_b64 v134, v[130:131], v[132:133] offset0:64 offset1:68
	v_cvt_pk_bf16_f32 v131, v88, v89
	v_cvt_pk_bf16_f32 v130, v86, v87
	v_cvt_pk_bf16_f32 v133, v84, v85
	v_cvt_pk_bf16_f32 v132, v82, v83
	ds_write2_b64 v134, v[130:131], v[132:133] offset0:96 offset1:100
	v_cvt_pk_bf16_f32 v131, v80, v81
	v_cvt_pk_bf16_f32 v130, v78, v79
	v_cvt_pk_bf16_f32 v133, v76, v77
	v_cvt_pk_bf16_f32 v132, v74, v75
	v_add_u32_e32 v134, 0x6000, v0
	ds_write2_b64 v134, v[130:131], v[132:133] offset0:96 offset1:100
	v_cvt_pk_bf16_f32 v131, v72, v73
	v_cvt_pk_bf16_f32 v130, v70, v71
	v_cvt_pk_bf16_f32 v133, v68, v69
	v_cvt_pk_bf16_f32 v132, v66, v67
	ds_write2_b64 v134, v[130:131], v[132:133] offset0:128 offset1:132
	v_cvt_pk_bf16_f32 v131, v64, v65
	v_cvt_pk_bf16_f32 v130, v62, v63
	v_cvt_pk_bf16_f32 v133, v60, v61
	v_cvt_pk_bf16_f32 v132, v58, v59
	v_add_u32_e32 v134, 0x8000, v0
	ds_write2_b64 v134, v[130:131], v[132:133] offset0:128 offset1:132
	v_cvt_pk_bf16_f32 v131, v56, v57
	v_cvt_pk_bf16_f32 v130, v54, v55
	v_cvt_pk_bf16_f32 v133, v52, v53
	v_cvt_pk_bf16_f32 v132, v50, v51
	ds_write2_b64 v134, v[130:131], v[132:133] offset0:160 offset1:164
	v_cvt_pk_bf16_f32 v131, v48, v49
	v_cvt_pk_bf16_f32 v130, v46, v47
	v_cvt_pk_bf16_f32 v133, v44, v45
	v_cvt_pk_bf16_f32 v132, v42, v43
	v_add_u32_e32 v134, 0xa000, v0
	ds_write2_b64 v134, v[130:131], v[132:133] offset0:160 offset1:164
	v_cvt_pk_bf16_f32 v131, v36, v37
	v_cvt_pk_bf16_f32 v130, v34, v35
	v_cvt_pk_bf16_f32 v133, v32, v33
	v_cvt_pk_bf16_f32 v132, v30, v31
	ds_write2_b64 v134, v[130:131], v[132:133] offset0:192 offset1:196
	v_cvt_pk_bf16_f32 v131, v40, v41
	v_cvt_pk_bf16_f32 v130, v38, v39
	v_cvt_pk_bf16_f32 v133, v28, v29
	v_cvt_pk_bf16_f32 v132, v26, v27
	v_add_u32_e32 v134, 0xc000, v0
	ds_write2_b64 v134, v[130:131], v[132:133] offset0:192 offset1:196
	v_cvt_pk_bf16_f32 v131, v24, v25
	v_cvt_pk_bf16_f32 v130, v22, v23
	v_cvt_pk_bf16_f32 v133, v20, v21
	v_cvt_pk_bf16_f32 v132, v18, v19
	ds_write2_b64 v134, v[130:131], v[132:133] offset0:224 offset1:228
	v_cvt_pk_bf16_f32 v131, v16, v17
	v_cvt_pk_bf16_f32 v130, v14, v15
	v_cvt_pk_bf16_f32 v133, v12, v13
	v_cvt_pk_bf16_f32 v132, v10, v11
	v_add_u32_e32 v134, 0xe000, v0
	ds_write2_b64 v134, v[130:131], v[132:133] offset0:224 offset1:228
	v_cvt_pk_bf16_f32 v131, v8, v9
	v_cvt_pk_bf16_f32 v130, v6, v7
	v_cvt_pk_bf16_f32 v133, v4, v5
	v_cvt_pk_bf16_f32 v132, v2, v3
	v_add_u32_e32 v0, 0xe800, v0
	ds_write2_b64 v0, v[130:131], v[132:133] offset1:4
	v_lshlrev_b32_e32 v0, 2, v175
	v_and_b32_e32 v0, 0x7c, v0
	s_mul_i32 s2, s28, 0x10800
	v_readlane_b32 s48, v253, 61
	v_lshl_or_b32 v164, s47, 7, v0
	s_mul_hi_u32 s3, s28, 0x10800
	v_readlane_b32 s49, v253, 62
	s_add_u32 s2, s48, s2
	v_ashrrev_i32_e32 v165, 31, v164
	s_addc_u32 s3, s49, s3
	v_lshlrev_b64 v[130:131], 2, v[164:165]
	v_lshl_add_u64 v[150:151], s[2:3], 0, v[130:131]
	s_movk_i32 s2, 0x5000
	v_add_co_u32_e32 v134, vcc, s2, v150
	s_mov_b32 s2, 0xb000
	s_nop 0
	v_addc_co_u32_e32 v135, vcc, 0, v151, vcc
	v_add_co_u32_e32 v138, vcc, s2, v150
	v_readlane_b32 s50, v253, 63
	s_nop 0
	v_addc_co_u32_e32 v139, vcc, 0, v151, vcc
	v_add_co_u32_e32 v142, vcc, s25, v150
	s_mul_i32 s4, s28, 0x5800
	s_nop 0
	v_addc_co_u32_e32 v143, vcc, 0, v151, vcc
	s_mov_b32 s2, 0x8000
	v_readlane_b32 s51, v254, 0
	s_mul_hi_u32 s5, s28, 0x5800
	s_add_u32 s4, s50, s4
	v_add_co_u32_e32 v146, vcc, s2, v150
	s_addc_u32 s5, s51, s5
	s_nop 0
	v_addc_co_u32_e32 v147, vcc, 0, v151, vcc
	s_mov_b32 s2, 0xd000
	s_waitcnt lgkmcnt(0)
	s_barrier
	v_lshl_add_u64 v[158:159], s[4:5], 0, v[130:131]
	global_load_dwordx4 v[130:133], v[150:151], off
	v_add_co_u32_e32 v150, vcc, s2, v150
	global_load_dwordx4 v[134:137], v[134:135], off offset:2048
	s_nop 0
	global_load_dwordx4 v[138:141], v[138:139], off
	v_addc_co_u32_e32 v151, vcc, 0, v151, vcc
	global_load_dwordx4 v[142:145], v[142:143], off offset:3072
	s_nop 0
	global_load_dwordx4 v[146:149], v[146:147], off offset:1024
	s_nop 0
	global_load_dwordx4 v[150:153], v[150:151], off offset:3072
	s_nop 0
	global_load_dwordx4 v[154:157], v[158:159], off
	v_add_co_u32_e32 v158, vcc, 0x2000, v158
	v_ashrrev_i32_e32 v0, 5, v175
	s_nop 0
	v_addc_co_u32_e32 v159, vcc, 0, v159, vcc
	global_load_dwordx4 v[158:161], v[158:159], off offset:3072
	v_readlane_b32 s2, v252, 32
	v_readlane_b32 s3, v252, 33
	v_mul_lo_u32 v166, v0, s15
	v_and_b32_e32 v167, 31, v175
	s_mov_b32 s14, 0
	v_lshl_add_u64 v[164:165], v[164:165], 1, s[2:3]
	v_lshl_add_u32 v166, v167, 3, v166
	v_add_u32_e32 v167, s40, v0
	s_waitcnt vmcnt(0)
	s_mov_b32 s14, 0x8800
	v_mul_u32_u24_e32 v63, 0x2100, v0
	v_and_b32_e32 v64, 31, v175
	v_lshl_add_u32 v63, v64, 3, v63
	v_lshlrev_b32_e32 v61, 4, v0
	v_add_u32_e32 v61, 1, v61
	v_add_u32_e32 v62, s40, v61
	s_mov_b32 s4, 0x78787879
	v_mul_hi_i32 v60, v62, s4
	v_lshrrev_b32_e32 v64, 31, v60
	v_ashrrev_i32_e32 v60, 11, v60
	v_add_u32_e32 v60, v60, v64
	v_mul_i32_i24_e32 v60, 0x1100, v60
	v_sub_u32_e32 v60, v62, v60
	s_movk_i32 s4, 0x1600
	v_mad_i64_i32 v[58:59], s[4:5], v62, s4, v[164:165]
	v_mov_b32_e32 v56, 0x1600
	v_mov_b32_e32 v57, 0
	ds_read2_b64 v[26:29], v63 offset1:32
	ds_read2_b64 v[68:71], v63 offset0:66 offset1:98
	s_waitcnt lgkmcnt(0)
	v_lshlrev_b32_e32 v2, 16, v26
	v_and_b32_e32 v3, 0xffff0000, v26
	v_lshlrev_b32_e32 v4, 16, v27
	v_and_b32_e32 v5, 0xffff0000, v27
	v_lshlrev_b32_e32 v14, 16, v28
	v_and_b32_e32 v15, 0xffff0000, v28
	v_lshlrev_b32_e32 v16, 16, v29
	v_and_b32_e32 v17, 0xffff0000, v29
	v_lshlrev_b32_e32 v6, 16, v68
	v_and_b32_e32 v7, 0xffff0000, v68
	v_lshlrev_b32_e32 v8, 16, v69
	v_and_b32_e32 v9, 0xffff0000, v69
	v_lshlrev_b32_e32 v18, 16, v70
	v_and_b32_e32 v19, 0xffff0000, v70
	v_lshlrev_b32_e32 v20, 16, v71
	v_and_b32_e32 v21, 0xffff0000, v71
	v_add_u32_e32 v63, 0x420, v63
	v_add_u32_e32 v64, -1, v60
	v_add_u32_e32 v65, 0xfffffeff, v60
	v_cmp_gt_u32_e32 vcc, 0xfef, v65
	s_mov_b64 s[4:5], vcc
	v_cmp_gt_u32_e32 vcc, 0xef, v64
	s_or_b64 s[4:5], s[4:5], vcc
	v_add_u32_e32 v64, 15, v62
	v_cmp_gt_i32_e32 vcc, s14, v64
	s_and_b64 s[4:5], s[4:5], vcc
	s_xor_b64 s[4:5], s[4:5], exec
	s_cmp_eq_u64 s[4:5], 0
	s_cbranch_scc0 .Lconv_slow
	v_cmp_gt_u32_e32 vcc, 15, v0
	ds_read2_b64 v[26:29], v63 offset1:32
	s_waitcnt lgkmcnt(0)
	v_lshlrev_b32_e32 v10, 16, v26
	v_and_b32_e32 v11, 0xffff0000, v26
	v_lshlrev_b32_e32 v12, 16, v27
	v_and_b32_e32 v13, 0xffff0000, v27
	v_lshlrev_b32_e32 v22, 16, v28
	v_and_b32_e32 v23, 0xffff0000, v28
	v_lshlrev_b32_e32 v24, 16, v29
	v_and_b32_e32 v25, 0xffff0000, v29
	v_add_u32_e32 v63, 0x210, v63
	ds_read2_b64 v[26:29], v63 offset1:32
	v_pk_fma_f32 v[30:31], v[146:147], v[18:19], v[158:159]
	v_pk_fma_f32 v[32:33], v[148:149], v[20:21], v[160:161]
	v_pk_fma_f32 v[34:35], v[134:135], v[6:7], v[154:155]
	v_pk_fma_f32 v[36:37], v[136:137], v[8:9], v[156:157]
	v_pk_fma_f32 v[30:31], v[142:143], v[14:15], v[30:31]
	v_pk_fma_f32 v[32:33], v[144:145], v[16:17], v[32:33]
	v_pk_fma_f32 v[34:35], v[130:131], v[2:3], v[34:35]
	v_pk_fma_f32 v[36:37], v[132:133], v[4:5], v[36:37]
	v_pk_fma_f32 v[30:31], v[150:151], v[22:23], v[30:31]
	v_pk_fma_f32 v[32:33], v[152:153], v[24:25], v[32:33]
	v_pk_fma_f32 v[34:35], v[138:139], v[10:11], v[34:35]
	v_pk_fma_f32 v[36:37], v[140:141], v[12:13], v[36:37]
	v_mul_f32_e32 v42, 0xbfb8aa3b, v30
	v_mul_f32_e32 v43, 0xbfb8aa3b, v31
	v_mul_f32_e32 v44, 0xbfb8aa3b, v32
	v_mul_f32_e32 v45, 0xbfb8aa3b, v33
	v_exp_f32_e32 v42, v42
	v_exp_f32_e32 v43, v43
	v_exp_f32_e32 v44, v44
	v_exp_f32_e32 v45, v45
	v_pk_add_f32 v[42:43], v[42:43], 1.0 op_sel_hi:[1,0]
	v_pk_add_f32 v[44:45], v[44:45], 1.0 op_sel_hi:[1,0]
	v_rcp_f32_e32 v46, v42
	v_rcp_f32_e32 v47, v43
	v_rcp_f32_e32 v48, v44
	v_rcp_f32_e32 v49, v45
	v_mul_f32_e32 v46, v30, v46
	v_mul_f32_e32 v47, v31, v47
	v_mul_f32_e32 v48, v32, v48
	v_mul_f32_e32 v49, v33, v49
	v_pk_mul_f32 v[34:35], v[34:35], v[46:47]
	v_pk_mul_f32 v[36:37], v[36:37], v[48:49]
	v_cvt_pk_bf16_f32 v66, v34, v35
	v_cvt_pk_bf16_f32 v67, v36, v37
	global_store_dwordx2 v[58:59], v[66:67], off
	v_lshl_add_u64 v[58:59], v[58:59], 0, v[56:57]
	s_waitcnt lgkmcnt(0)
	v_lshlrev_b32_e32 v2, 16, v26
	v_and_b32_e32 v3, 0xffff0000, v26
	v_lshlrev_b32_e32 v4, 16, v27
	v_and_b32_e32 v5, 0xffff0000, v27
	v_lshlrev_b32_e32 v14, 16, v28
	v_and_b32_e32 v15, 0xffff0000, v28
	v_lshlrev_b32_e32 v16, 16, v29
	v_and_b32_e32 v17, 0xffff0000, v29
	v_add_u32_e32 v63, 0x210, v63
	ds_read2_b64 v[26:29], v63 offset1:32
	v_pk_fma_f32 v[30:31], v[146:147], v[22:23], v[158:159]
	v_pk_fma_f32 v[32:33], v[148:149], v[24:25], v[160:161]
	v_pk_fma_f32 v[34:35], v[134:135], v[10:11], v[154:155]
	v_pk_fma_f32 v[36:37], v[136:137], v[12:13], v[156:157]
	v_pk_fma_f32 v[30:31], v[142:143], v[18:19], v[30:31]
	v_pk_fma_f32 v[32:33], v[144:145], v[20:21], v[32:33]
	v_pk_fma_f32 v[34:35], v[130:131], v[6:7], v[34:35]
	v_pk_fma_f32 v[36:37], v[132:133], v[8:9], v[36:37]
	v_pk_fma_f32 v[30:31], v[150:151], v[14:15], v[30:31]
	v_pk_fma_f32 v[32:33], v[152:153], v[16:17], v[32:33]
	v_pk_fma_f32 v[34:35], v[138:139], v[2:3], v[34:35]
	v_pk_fma_f32 v[36:37], v[140:141], v[4:5], v[36:37]
	v_mul_f32_e32 v42, 0xbfb8aa3b, v30
	v_mul_f32_e32 v43, 0xbfb8aa3b, v31
	v_mul_f32_e32 v44, 0xbfb8aa3b, v32
	v_mul_f32_e32 v45, 0xbfb8aa3b, v33
	v_exp_f32_e32 v42, v42
	v_exp_f32_e32 v43, v43
	v_exp_f32_e32 v44, v44
	v_exp_f32_e32 v45, v45
	v_pk_add_f32 v[42:43], v[42:43], 1.0 op_sel_hi:[1,0]
	v_pk_add_f32 v[44:45], v[44:45], 1.0 op_sel_hi:[1,0]
	v_rcp_f32_e32 v46, v42
	v_rcp_f32_e32 v47, v43
	v_rcp_f32_e32 v48, v44
	v_rcp_f32_e32 v49, v45
	v_mul_f32_e32 v46, v30, v46
	v_mul_f32_e32 v47, v31, v47
	v_mul_f32_e32 v48, v32, v48
	v_mul_f32_e32 v49, v33, v49
	v_pk_mul_f32 v[34:35], v[34:35], v[46:47]
	v_pk_mul_f32 v[36:37], v[36:37], v[48:49]
	v_cvt_pk_bf16_f32 v66, v34, v35
	v_cvt_pk_bf16_f32 v67, v36, v37
	global_store_dwordx2 v[58:59], v[66:67], off
	v_lshl_add_u64 v[58:59], v[58:59], 0, v[56:57]
	s_waitcnt lgkmcnt(0)
	v_lshlrev_b32_e32 v6, 16, v26
	v_and_b32_e32 v7, 0xffff0000, v26
	v_lshlrev_b32_e32 v8, 16, v27
	v_and_b32_e32 v9, 0xffff0000, v27
	v_lshlrev_b32_e32 v18, 16, v28
	v_and_b32_e32 v19, 0xffff0000, v28
	v_lshlrev_b32_e32 v20, 16, v29
	v_and_b32_e32 v21, 0xffff0000, v29
	v_add_u32_e32 v63, 0x210, v63
	ds_read2_b64 v[26:29], v63 offset1:32
	v_pk_fma_f32 v[30:31], v[146:147], v[14:15], v[158:159]
	v_pk_fma_f32 v[32:33], v[148:149], v[16:17], v[160:161]
	v_pk_fma_f32 v[34:35], v[134:135], v[2:3], v[154:155]
	v_pk_fma_f32 v[36:37], v[136:137], v[4:5], v[156:157]
	v_pk_fma_f32 v[30:31], v[142:143], v[22:23], v[30:31]
	v_pk_fma_f32 v[32:33], v[144:145], v[24:25], v[32:33]
	v_pk_fma_f32 v[34:35], v[130:131], v[10:11], v[34:35]
	v_pk_fma_f32 v[36:37], v[132:133], v[12:13], v[36:37]
	v_pk_fma_f32 v[30:31], v[150:151], v[18:19], v[30:31]
	v_pk_fma_f32 v[32:33], v[152:153], v[20:21], v[32:33]
	v_pk_fma_f32 v[34:35], v[138:139], v[6:7], v[34:35]
	v_pk_fma_f32 v[36:37], v[140:141], v[8:9], v[36:37]
	v_mul_f32_e32 v42, 0xbfb8aa3b, v30
	v_mul_f32_e32 v43, 0xbfb8aa3b, v31
	v_mul_f32_e32 v44, 0xbfb8aa3b, v32
	v_mul_f32_e32 v45, 0xbfb8aa3b, v33
	v_exp_f32_e32 v42, v42
	v_exp_f32_e32 v43, v43
	v_exp_f32_e32 v44, v44
	v_exp_f32_e32 v45, v45
	v_pk_add_f32 v[42:43], v[42:43], 1.0 op_sel_hi:[1,0]
	v_pk_add_f32 v[44:45], v[44:45], 1.0 op_sel_hi:[1,0]
	v_rcp_f32_e32 v46, v42
	v_rcp_f32_e32 v47, v43
	v_rcp_f32_e32 v48, v44
	v_rcp_f32_e32 v49, v45
	v_mul_f32_e32 v46, v30, v46
	v_mul_f32_e32 v47, v31, v47
	v_mul_f32_e32 v48, v32, v48
	v_mul_f32_e32 v49, v33, v49
	v_pk_mul_f32 v[34:35], v[34:35], v[46:47]
	v_pk_mul_f32 v[36:37], v[36:37], v[48:49]
	v_cvt_pk_bf16_f32 v66, v34, v35
	v_cvt_pk_bf16_f32 v67, v36, v37
	global_store_dwordx2 v[58:59], v[66:67], off
	v_lshl_add_u64 v[58:59], v[58:59], 0, v[56:57]
	s_waitcnt lgkmcnt(0)
	v_lshlrev_b32_e32 v10, 16, v26
	v_and_b32_e32 v11, 0xffff0000, v26
	v_lshlrev_b32_e32 v12, 16, v27
	v_and_b32_e32 v13, 0xffff0000, v27
	v_lshlrev_b32_e32 v22, 16, v28
	v_and_b32_e32 v23, 0xffff0000, v28
	v_lshlrev_b32_e32 v24, 16, v29
	v_and_b32_e32 v25, 0xffff0000, v29
	v_add_u32_e32 v63, 0x210, v63
	ds_read2_b64 v[26:29], v63 offset1:32
	v_pk_fma_f32 v[30:31], v[146:147], v[18:19], v[158:159]
	v_pk_fma_f32 v[32:33], v[148:149], v[20:21], v[160:161]
	v_pk_fma_f32 v[34:35], v[134:135], v[6:7], v[154:155]
	v_pk_fma_f32 v[36:37], v[136:137], v[8:9], v[156:157]
	v_pk_fma_f32 v[30:31], v[142:143], v[14:15], v[30:31]
	v_pk_fma_f32 v[32:33], v[144:145], v[16:17], v[32:33]
	v_pk_fma_f32 v[34:35], v[130:131], v[2:3], v[34:35]
	v_pk_fma_f32 v[36:37], v[132:133], v[4:5], v[36:37]
	v_pk_fma_f32 v[30:31], v[150:151], v[22:23], v[30:31]
	v_pk_fma_f32 v[32:33], v[152:153], v[24:25], v[32:33]
	v_pk_fma_f32 v[34:35], v[138:139], v[10:11], v[34:35]
	v_pk_fma_f32 v[36:37], v[140:141], v[12:13], v[36:37]
	v_mul_f32_e32 v42, 0xbfb8aa3b, v30
	v_mul_f32_e32 v43, 0xbfb8aa3b, v31
	v_mul_f32_e32 v44, 0xbfb8aa3b, v32
	v_mul_f32_e32 v45, 0xbfb8aa3b, v33
	v_exp_f32_e32 v42, v42
	v_exp_f32_e32 v43, v43
	v_exp_f32_e32 v44, v44
	v_exp_f32_e32 v45, v45
	v_pk_add_f32 v[42:43], v[42:43], 1.0 op_sel_hi:[1,0]
	v_pk_add_f32 v[44:45], v[44:45], 1.0 op_sel_hi:[1,0]
	v_rcp_f32_e32 v46, v42
	v_rcp_f32_e32 v47, v43
	v_rcp_f32_e32 v48, v44
	v_rcp_f32_e32 v49, v45
	v_mul_f32_e32 v46, v30, v46
	v_mul_f32_e32 v47, v31, v47
	v_mul_f32_e32 v48, v32, v48
	v_mul_f32_e32 v49, v33, v49
	v_pk_mul_f32 v[34:35], v[34:35], v[46:47]
	v_pk_mul_f32 v[36:37], v[36:37], v[48:49]
	v_cvt_pk_bf16_f32 v66, v34, v35
	v_cvt_pk_bf16_f32 v67, v36, v37
	global_store_dwordx2 v[58:59], v[66:67], off
	v_lshl_add_u64 v[58:59], v[58:59], 0, v[56:57]
	s_waitcnt lgkmcnt(0)
	v_lshlrev_b32_e32 v2, 16, v26
	v_and_b32_e32 v3, 0xffff0000, v26
	v_lshlrev_b32_e32 v4, 16, v27
	v_and_b32_e32 v5, 0xffff0000, v27
	v_lshlrev_b32_e32 v14, 16, v28
	v_and_b32_e32 v15, 0xffff0000, v28
	v_lshlrev_b32_e32 v16, 16, v29
	v_and_b32_e32 v17, 0xffff0000, v29
	v_add_u32_e32 v63, 0x210, v63
	ds_read2_b64 v[26:29], v63 offset1:32
	v_pk_fma_f32 v[30:31], v[146:147], v[22:23], v[158:159]
	v_pk_fma_f32 v[32:33], v[148:149], v[24:25], v[160:161]
	v_pk_fma_f32 v[34:35], v[134:135], v[10:11], v[154:155]
	v_pk_fma_f32 v[36:37], v[136:137], v[12:13], v[156:157]
	v_pk_fma_f32 v[30:31], v[142:143], v[18:19], v[30:31]
	v_pk_fma_f32 v[32:33], v[144:145], v[20:21], v[32:33]
	v_pk_fma_f32 v[34:35], v[130:131], v[6:7], v[34:35]
	v_pk_fma_f32 v[36:37], v[132:133], v[8:9], v[36:37]
	v_pk_fma_f32 v[30:31], v[150:151], v[14:15], v[30:31]
	v_pk_fma_f32 v[32:33], v[152:153], v[16:17], v[32:33]
	v_pk_fma_f32 v[34:35], v[138:139], v[2:3], v[34:35]
	v_pk_fma_f32 v[36:37], v[140:141], v[4:5], v[36:37]
	v_mul_f32_e32 v42, 0xbfb8aa3b, v30
	v_mul_f32_e32 v43, 0xbfb8aa3b, v31
	v_mul_f32_e32 v44, 0xbfb8aa3b, v32
	v_mul_f32_e32 v45, 0xbfb8aa3b, v33
	v_exp_f32_e32 v42, v42
	v_exp_f32_e32 v43, v43
	v_exp_f32_e32 v44, v44
	v_exp_f32_e32 v45, v45
	v_pk_add_f32 v[42:43], v[42:43], 1.0 op_sel_hi:[1,0]
	v_pk_add_f32 v[44:45], v[44:45], 1.0 op_sel_hi:[1,0]
	v_rcp_f32_e32 v46, v42
	v_rcp_f32_e32 v47, v43
	v_rcp_f32_e32 v48, v44
	v_rcp_f32_e32 v49, v45
	v_mul_f32_e32 v46, v30, v46
	v_mul_f32_e32 v47, v31, v47
	v_mul_f32_e32 v48, v32, v48
	v_mul_f32_e32 v49, v33, v49
	v_pk_mul_f32 v[34:35], v[34:35], v[46:47]
	v_pk_mul_f32 v[36:37], v[36:37], v[48:49]
	v_cvt_pk_bf16_f32 v66, v34, v35
	v_cvt_pk_bf16_f32 v67, v36, v37
	global_store_dwordx2 v[58:59], v[66:67], off
	v_lshl_add_u64 v[58:59], v[58:59], 0, v[56:57]
	s_waitcnt lgkmcnt(0)
	v_lshlrev_b32_e32 v6, 16, v26
	v_and_b32_e32 v7, 0xffff0000, v26
	v_lshlrev_b32_e32 v8, 16, v27
	v_and_b32_e32 v9, 0xffff0000, v27
	v_lshlrev_b32_e32 v18, 16, v28
	v_and_b32_e32 v19, 0xffff0000, v28
	v_lshlrev_b32_e32 v20, 16, v29
	v_and_b32_e32 v21, 0xffff0000, v29
	v_add_u32_e32 v63, 0x210, v63
	ds_read2_b64 v[26:29], v63 offset1:32
	v_pk_fma_f32 v[30:31], v[146:147], v[14:15], v[158:159]
	v_pk_fma_f32 v[32:33], v[148:149], v[16:17], v[160:161]
	v_pk_fma_f32 v[34:35], v[134:135], v[2:3], v[154:155]
	v_pk_fma_f32 v[36:37], v[136:137], v[4:5], v[156:157]
	v_pk_fma_f32 v[30:31], v[142:143], v[22:23], v[30:31]
	v_pk_fma_f32 v[32:33], v[144:145], v[24:25], v[32:33]
	v_pk_fma_f32 v[34:35], v[130:131], v[10:11], v[34:35]
	v_pk_fma_f32 v[36:37], v[132:133], v[12:13], v[36:37]
	v_pk_fma_f32 v[30:31], v[150:151], v[18:19], v[30:31]
	v_pk_fma_f32 v[32:33], v[152:153], v[20:21], v[32:33]
	v_pk_fma_f32 v[34:35], v[138:139], v[6:7], v[34:35]
	v_pk_fma_f32 v[36:37], v[140:141], v[8:9], v[36:37]
	v_mul_f32_e32 v42, 0xbfb8aa3b, v30
	v_mul_f32_e32 v43, 0xbfb8aa3b, v31
	v_mul_f32_e32 v44, 0xbfb8aa3b, v32
	v_mul_f32_e32 v45, 0xbfb8aa3b, v33
	v_exp_f32_e32 v42, v42
	v_exp_f32_e32 v43, v43
	v_exp_f32_e32 v44, v44
	v_exp_f32_e32 v45, v45
	v_pk_add_f32 v[42:43], v[42:43], 1.0 op_sel_hi:[1,0]
	v_pk_add_f32 v[44:45], v[44:45], 1.0 op_sel_hi:[1,0]
	v_rcp_f32_e32 v46, v42
	v_rcp_f32_e32 v47, v43
	v_rcp_f32_e32 v48, v44
	v_rcp_f32_e32 v49, v45
	v_mul_f32_e32 v46, v30, v46
	v_mul_f32_e32 v47, v31, v47
	v_mul_f32_e32 v48, v32, v48
	v_mul_f32_e32 v49, v33, v49
	v_pk_mul_f32 v[34:35], v[34:35], v[46:47]
	v_pk_mul_f32 v[36:37], v[36:37], v[48:49]
	v_cvt_pk_bf16_f32 v66, v34, v35
	v_cvt_pk_bf16_f32 v67, v36, v37
	global_store_dwordx2 v[58:59], v[66:67], off
	v_lshl_add_u64 v[58:59], v[58:59], 0, v[56:57]
	s_waitcnt lgkmcnt(0)
	v_lshlrev_b32_e32 v10, 16, v26
	v_and_b32_e32 v11, 0xffff0000, v26
	v_lshlrev_b32_e32 v12, 16, v27
	v_and_b32_e32 v13, 0xffff0000, v27
	v_lshlrev_b32_e32 v22, 16, v28
	v_and_b32_e32 v23, 0xffff0000, v28
	v_lshlrev_b32_e32 v24, 16, v29
	v_and_b32_e32 v25, 0xffff0000, v29
	v_add_u32_e32 v63, 0x210, v63
	ds_read2_b64 v[26:29], v63 offset1:32
	v_pk_fma_f32 v[30:31], v[146:147], v[18:19], v[158:159]
	v_pk_fma_f32 v[32:33], v[148:149], v[20:21], v[160:161]
	v_pk_fma_f32 v[34:35], v[134:135], v[6:7], v[154:155]
	v_pk_fma_f32 v[36:37], v[136:137], v[8:9], v[156:157]
	v_pk_fma_f32 v[30:31], v[142:143], v[14:15], v[30:31]
	v_pk_fma_f32 v[32:33], v[144:145], v[16:17], v[32:33]
	v_pk_fma_f32 v[34:35], v[130:131], v[2:3], v[34:35]
	v_pk_fma_f32 v[36:37], v[132:133], v[4:5], v[36:37]
	v_pk_fma_f32 v[30:31], v[150:151], v[22:23], v[30:31]
	v_pk_fma_f32 v[32:33], v[152:153], v[24:25], v[32:33]
	v_pk_fma_f32 v[34:35], v[138:139], v[10:11], v[34:35]
	v_pk_fma_f32 v[36:37], v[140:141], v[12:13], v[36:37]
	v_mul_f32_e32 v42, 0xbfb8aa3b, v30
	v_mul_f32_e32 v43, 0xbfb8aa3b, v31
	v_mul_f32_e32 v44, 0xbfb8aa3b, v32
	v_mul_f32_e32 v45, 0xbfb8aa3b, v33
	v_exp_f32_e32 v42, v42
	v_exp_f32_e32 v43, v43
	v_exp_f32_e32 v44, v44
	v_exp_f32_e32 v45, v45
	v_pk_add_f32 v[42:43], v[42:43], 1.0 op_sel_hi:[1,0]
	v_pk_add_f32 v[44:45], v[44:45], 1.0 op_sel_hi:[1,0]
	v_rcp_f32_e32 v46, v42
	v_rcp_f32_e32 v47, v43
	v_rcp_f32_e32 v48, v44
	v_rcp_f32_e32 v49, v45
	v_mul_f32_e32 v46, v30, v46
	v_mul_f32_e32 v47, v31, v47
	v_mul_f32_e32 v48, v32, v48
	v_mul_f32_e32 v49, v33, v49
	v_pk_mul_f32 v[34:35], v[34:35], v[46:47]
	v_pk_mul_f32 v[36:37], v[36:37], v[48:49]
	v_cvt_pk_bf16_f32 v66, v34, v35
	v_cvt_pk_bf16_f32 v67, v36, v37
	global_store_dwordx2 v[58:59], v[66:67], off
	v_lshl_add_u64 v[58:59], v[58:59], 0, v[56:57]
	s_waitcnt lgkmcnt(0)
	v_lshlrev_b32_e32 v2, 16, v26
	v_and_b32_e32 v3, 0xffff0000, v26
	v_lshlrev_b32_e32 v4, 16, v27
	v_and_b32_e32 v5, 0xffff0000, v27
	v_lshlrev_b32_e32 v14, 16, v28
	v_and_b32_e32 v15, 0xffff0000, v28
	v_lshlrev_b32_e32 v16, 16, v29
	v_and_b32_e32 v17, 0xffff0000, v29
	v_add_u32_e32 v63, 0x210, v63
	ds_read2_b64 v[26:29], v63 offset1:32
	v_pk_fma_f32 v[30:31], v[146:147], v[22:23], v[158:159]
	v_pk_fma_f32 v[32:33], v[148:149], v[24:25], v[160:161]
	v_pk_fma_f32 v[34:35], v[134:135], v[10:11], v[154:155]
	v_pk_fma_f32 v[36:37], v[136:137], v[12:13], v[156:157]
	v_pk_fma_f32 v[30:31], v[142:143], v[18:19], v[30:31]
	v_pk_fma_f32 v[32:33], v[144:145], v[20:21], v[32:33]
	v_pk_fma_f32 v[34:35], v[130:131], v[6:7], v[34:35]
	v_pk_fma_f32 v[36:37], v[132:133], v[8:9], v[36:37]
	v_pk_fma_f32 v[30:31], v[150:151], v[14:15], v[30:31]
	v_pk_fma_f32 v[32:33], v[152:153], v[16:17], v[32:33]
	v_pk_fma_f32 v[34:35], v[138:139], v[2:3], v[34:35]
	v_pk_fma_f32 v[36:37], v[140:141], v[4:5], v[36:37]
	v_mul_f32_e32 v42, 0xbfb8aa3b, v30
	v_mul_f32_e32 v43, 0xbfb8aa3b, v31
	v_mul_f32_e32 v44, 0xbfb8aa3b, v32
	v_mul_f32_e32 v45, 0xbfb8aa3b, v33
	v_exp_f32_e32 v42, v42
	v_exp_f32_e32 v43, v43
	v_exp_f32_e32 v44, v44
	v_exp_f32_e32 v45, v45
	v_pk_add_f32 v[42:43], v[42:43], 1.0 op_sel_hi:[1,0]
	v_pk_add_f32 v[44:45], v[44:45], 1.0 op_sel_hi:[1,0]
	v_rcp_f32_e32 v46, v42
	v_rcp_f32_e32 v47, v43
	v_rcp_f32_e32 v48, v44
	v_rcp_f32_e32 v49, v45
	v_mul_f32_e32 v46, v30, v46
	v_mul_f32_e32 v47, v31, v47
	v_mul_f32_e32 v48, v32, v48
	v_mul_f32_e32 v49, v33, v49
	v_pk_mul_f32 v[34:35], v[34:35], v[46:47]
	v_pk_mul_f32 v[36:37], v[36:37], v[48:49]
	v_cvt_pk_bf16_f32 v66, v34, v35
	v_cvt_pk_bf16_f32 v67, v36, v37
	global_store_dwordx2 v[58:59], v[66:67], off
	v_lshl_add_u64 v[58:59], v[58:59], 0, v[56:57]
	s_waitcnt lgkmcnt(0)
	v_lshlrev_b32_e32 v6, 16, v26
	v_and_b32_e32 v7, 0xffff0000, v26
	v_lshlrev_b32_e32 v8, 16, v27
	v_and_b32_e32 v9, 0xffff0000, v27
	v_lshlrev_b32_e32 v18, 16, v28
	v_and_b32_e32 v19, 0xffff0000, v28
	v_lshlrev_b32_e32 v20, 16, v29
	v_and_b32_e32 v21, 0xffff0000, v29
	v_add_u32_e32 v63, 0x210, v63
	ds_read2_b64 v[26:29], v63 offset1:32
	v_pk_fma_f32 v[30:31], v[146:147], v[14:15], v[158:159]
	v_pk_fma_f32 v[32:33], v[148:149], v[16:17], v[160:161]
	v_pk_fma_f32 v[34:35], v[134:135], v[2:3], v[154:155]
	v_pk_fma_f32 v[36:37], v[136:137], v[4:5], v[156:157]
	v_pk_fma_f32 v[30:31], v[142:143], v[22:23], v[30:31]
	v_pk_fma_f32 v[32:33], v[144:145], v[24:25], v[32:33]
	v_pk_fma_f32 v[34:35], v[130:131], v[10:11], v[34:35]
	v_pk_fma_f32 v[36:37], v[132:133], v[12:13], v[36:37]
	v_pk_fma_f32 v[30:31], v[150:151], v[18:19], v[30:31]
	v_pk_fma_f32 v[32:33], v[152:153], v[20:21], v[32:33]
	v_pk_fma_f32 v[34:35], v[138:139], v[6:7], v[34:35]
	v_pk_fma_f32 v[36:37], v[140:141], v[8:9], v[36:37]
	v_mul_f32_e32 v42, 0xbfb8aa3b, v30
	v_mul_f32_e32 v43, 0xbfb8aa3b, v31
	v_mul_f32_e32 v44, 0xbfb8aa3b, v32
	v_mul_f32_e32 v45, 0xbfb8aa3b, v33
	v_exp_f32_e32 v42, v42
	v_exp_f32_e32 v43, v43
	v_exp_f32_e32 v44, v44
	v_exp_f32_e32 v45, v45
	v_pk_add_f32 v[42:43], v[42:43], 1.0 op_sel_hi:[1,0]
	v_pk_add_f32 v[44:45], v[44:45], 1.0 op_sel_hi:[1,0]
	v_rcp_f32_e32 v46, v42
	v_rcp_f32_e32 v47, v43
	v_rcp_f32_e32 v48, v44
	v_rcp_f32_e32 v49, v45
	v_mul_f32_e32 v46, v30, v46
	v_mul_f32_e32 v47, v31, v47
	v_mul_f32_e32 v48, v32, v48
	v_mul_f32_e32 v49, v33, v49
	v_pk_mul_f32 v[34:35], v[34:35], v[46:47]
	v_pk_mul_f32 v[36:37], v[36:37], v[48:49]
	v_cvt_pk_bf16_f32 v66, v34, v35
	v_cvt_pk_bf16_f32 v67, v36, v37
	global_store_dwordx2 v[58:59], v[66:67], off
	v_lshl_add_u64 v[58:59], v[58:59], 0, v[56:57]
	s_waitcnt lgkmcnt(0)
	v_lshlrev_b32_e32 v10, 16, v26
	v_and_b32_e32 v11, 0xffff0000, v26
	v_lshlrev_b32_e32 v12, 16, v27
	v_and_b32_e32 v13, 0xffff0000, v27
	v_lshlrev_b32_e32 v22, 16, v28
	v_and_b32_e32 v23, 0xffff0000, v28
	v_lshlrev_b32_e32 v24, 16, v29
	v_and_b32_e32 v25, 0xffff0000, v29
	v_add_u32_e32 v63, 0x210, v63
	ds_read2_b64 v[26:29], v63 offset1:32
	v_pk_fma_f32 v[30:31], v[146:147], v[18:19], v[158:159]
	v_pk_fma_f32 v[32:33], v[148:149], v[20:21], v[160:161]
	v_pk_fma_f32 v[34:35], v[134:135], v[6:7], v[154:155]
	v_pk_fma_f32 v[36:37], v[136:137], v[8:9], v[156:157]
	v_pk_fma_f32 v[30:31], v[142:143], v[14:15], v[30:31]
	v_pk_fma_f32 v[32:33], v[144:145], v[16:17], v[32:33]
	v_pk_fma_f32 v[34:35], v[130:131], v[2:3], v[34:35]
	v_pk_fma_f32 v[36:37], v[132:133], v[4:5], v[36:37]
	v_pk_fma_f32 v[30:31], v[150:151], v[22:23], v[30:31]
	v_pk_fma_f32 v[32:33], v[152:153], v[24:25], v[32:33]
	v_pk_fma_f32 v[34:35], v[138:139], v[10:11], v[34:35]
	v_pk_fma_f32 v[36:37], v[140:141], v[12:13], v[36:37]
	v_mul_f32_e32 v42, 0xbfb8aa3b, v30
	v_mul_f32_e32 v43, 0xbfb8aa3b, v31
	v_mul_f32_e32 v44, 0xbfb8aa3b, v32
	v_mul_f32_e32 v45, 0xbfb8aa3b, v33
	v_exp_f32_e32 v42, v42
	v_exp_f32_e32 v43, v43
	v_exp_f32_e32 v44, v44
	v_exp_f32_e32 v45, v45
	v_pk_add_f32 v[42:43], v[42:43], 1.0 op_sel_hi:[1,0]
	v_pk_add_f32 v[44:45], v[44:45], 1.0 op_sel_hi:[1,0]
	v_rcp_f32_e32 v46, v42
	v_rcp_f32_e32 v47, v43
	v_rcp_f32_e32 v48, v44
	v_rcp_f32_e32 v49, v45
	v_mul_f32_e32 v46, v30, v46
	v_mul_f32_e32 v47, v31, v47
	v_mul_f32_e32 v48, v32, v48
	v_mul_f32_e32 v49, v33, v49
	v_pk_mul_f32 v[34:35], v[34:35], v[46:47]
	v_pk_mul_f32 v[36:37], v[36:37], v[48:49]
	v_cvt_pk_bf16_f32 v66, v34, v35
	v_cvt_pk_bf16_f32 v67, v36, v37
	global_store_dwordx2 v[58:59], v[66:67], off
	v_lshl_add_u64 v[58:59], v[58:59], 0, v[56:57]
	s_waitcnt lgkmcnt(0)
	v_lshlrev_b32_e32 v2, 16, v26
	v_and_b32_e32 v3, 0xffff0000, v26
	v_lshlrev_b32_e32 v4, 16, v27
	v_and_b32_e32 v5, 0xffff0000, v27
	v_lshlrev_b32_e32 v14, 16, v28
	v_and_b32_e32 v15, 0xffff0000, v28
	v_lshlrev_b32_e32 v16, 16, v29
	v_and_b32_e32 v17, 0xffff0000, v29
	v_add_u32_e32 v63, 0x210, v63
	ds_read2_b64 v[26:29], v63 offset1:32
	v_pk_fma_f32 v[30:31], v[146:147], v[22:23], v[158:159]
	v_pk_fma_f32 v[32:33], v[148:149], v[24:25], v[160:161]
	v_pk_fma_f32 v[34:35], v[134:135], v[10:11], v[154:155]
	v_pk_fma_f32 v[36:37], v[136:137], v[12:13], v[156:157]
	v_pk_fma_f32 v[30:31], v[142:143], v[18:19], v[30:31]
	v_pk_fma_f32 v[32:33], v[144:145], v[20:21], v[32:33]
	v_pk_fma_f32 v[34:35], v[130:131], v[6:7], v[34:35]
	v_pk_fma_f32 v[36:37], v[132:133], v[8:9], v[36:37]
	v_pk_fma_f32 v[30:31], v[150:151], v[14:15], v[30:31]
	v_pk_fma_f32 v[32:33], v[152:153], v[16:17], v[32:33]
	v_pk_fma_f32 v[34:35], v[138:139], v[2:3], v[34:35]
	v_pk_fma_f32 v[36:37], v[140:141], v[4:5], v[36:37]
	v_mul_f32_e32 v42, 0xbfb8aa3b, v30
	v_mul_f32_e32 v43, 0xbfb8aa3b, v31
	v_mul_f32_e32 v44, 0xbfb8aa3b, v32
	v_mul_f32_e32 v45, 0xbfb8aa3b, v33
	v_exp_f32_e32 v42, v42
	v_exp_f32_e32 v43, v43
	v_exp_f32_e32 v44, v44
	v_exp_f32_e32 v45, v45
	v_pk_add_f32 v[42:43], v[42:43], 1.0 op_sel_hi:[1,0]
	v_pk_add_f32 v[44:45], v[44:45], 1.0 op_sel_hi:[1,0]
	v_rcp_f32_e32 v46, v42
	v_rcp_f32_e32 v47, v43
	v_rcp_f32_e32 v48, v44
	v_rcp_f32_e32 v49, v45
	v_mul_f32_e32 v46, v30, v46
	v_mul_f32_e32 v47, v31, v47
	v_mul_f32_e32 v48, v32, v48
	v_mul_f32_e32 v49, v33, v49
	v_pk_mul_f32 v[34:35], v[34:35], v[46:47]
	v_pk_mul_f32 v[36:37], v[36:37], v[48:49]
	v_cvt_pk_bf16_f32 v66, v34, v35
	v_cvt_pk_bf16_f32 v67, v36, v37
	global_store_dwordx2 v[58:59], v[66:67], off
	v_lshl_add_u64 v[58:59], v[58:59], 0, v[56:57]
	s_waitcnt lgkmcnt(0)
	v_lshlrev_b32_e32 v6, 16, v26
	v_and_b32_e32 v7, 0xffff0000, v26
	v_lshlrev_b32_e32 v8, 16, v27
	v_and_b32_e32 v9, 0xffff0000, v27
	v_lshlrev_b32_e32 v18, 16, v28
	v_and_b32_e32 v19, 0xffff0000, v28
	v_lshlrev_b32_e32 v20, 16, v29
	v_and_b32_e32 v21, 0xffff0000, v29
	v_add_u32_e32 v63, 0x210, v63
	ds_read2_b64 v[26:29], v63 offset1:32
	v_pk_fma_f32 v[30:31], v[146:147], v[14:15], v[158:159]
	v_pk_fma_f32 v[32:33], v[148:149], v[16:17], v[160:161]
	v_pk_fma_f32 v[34:35], v[134:135], v[2:3], v[154:155]
	v_pk_fma_f32 v[36:37], v[136:137], v[4:5], v[156:157]
	v_pk_fma_f32 v[30:31], v[142:143], v[22:23], v[30:31]
	v_pk_fma_f32 v[32:33], v[144:145], v[24:25], v[32:33]
	v_pk_fma_f32 v[34:35], v[130:131], v[10:11], v[34:35]
	v_pk_fma_f32 v[36:37], v[132:133], v[12:13], v[36:37]
	v_pk_fma_f32 v[30:31], v[150:151], v[18:19], v[30:31]
	v_pk_fma_f32 v[32:33], v[152:153], v[20:21], v[32:33]
	v_pk_fma_f32 v[34:35], v[138:139], v[6:7], v[34:35]
	v_pk_fma_f32 v[36:37], v[140:141], v[8:9], v[36:37]
	v_mul_f32_e32 v42, 0xbfb8aa3b, v30
	v_mul_f32_e32 v43, 0xbfb8aa3b, v31
	v_mul_f32_e32 v44, 0xbfb8aa3b, v32
	v_mul_f32_e32 v45, 0xbfb8aa3b, v33
	v_exp_f32_e32 v42, v42
	v_exp_f32_e32 v43, v43
	v_exp_f32_e32 v44, v44
	v_exp_f32_e32 v45, v45
	v_pk_add_f32 v[42:43], v[42:43], 1.0 op_sel_hi:[1,0]
	v_pk_add_f32 v[44:45], v[44:45], 1.0 op_sel_hi:[1,0]
	v_rcp_f32_e32 v46, v42
	v_rcp_f32_e32 v47, v43
	v_rcp_f32_e32 v48, v44
	v_rcp_f32_e32 v49, v45
	v_mul_f32_e32 v46, v30, v46
	v_mul_f32_e32 v47, v31, v47
	v_mul_f32_e32 v48, v32, v48
	v_mul_f32_e32 v49, v33, v49
	v_pk_mul_f32 v[34:35], v[34:35], v[46:47]
	v_pk_mul_f32 v[36:37], v[36:37], v[48:49]
	v_cvt_pk_bf16_f32 v66, v34, v35
	v_cvt_pk_bf16_f32 v67, v36, v37
	global_store_dwordx2 v[58:59], v[66:67], off
	v_lshl_add_u64 v[58:59], v[58:59], 0, v[56:57]
	s_waitcnt lgkmcnt(0)
	v_lshlrev_b32_e32 v10, 16, v26
	v_and_b32_e32 v11, 0xffff0000, v26
	v_lshlrev_b32_e32 v12, 16, v27
	v_and_b32_e32 v13, 0xffff0000, v27
	v_lshlrev_b32_e32 v22, 16, v28
	v_and_b32_e32 v23, 0xffff0000, v28
	v_lshlrev_b32_e32 v24, 16, v29
	v_and_b32_e32 v25, 0xffff0000, v29
	v_add_u32_e32 v63, 0x210, v63
	ds_read2_b64 v[26:29], v63 offset1:32
	v_pk_fma_f32 v[30:31], v[146:147], v[18:19], v[158:159]
	v_pk_fma_f32 v[32:33], v[148:149], v[20:21], v[160:161]
	v_pk_fma_f32 v[34:35], v[134:135], v[6:7], v[154:155]
	v_pk_fma_f32 v[36:37], v[136:137], v[8:9], v[156:157]
	v_pk_fma_f32 v[30:31], v[142:143], v[14:15], v[30:31]
	v_pk_fma_f32 v[32:33], v[144:145], v[16:17], v[32:33]
	v_pk_fma_f32 v[34:35], v[130:131], v[2:3], v[34:35]
	v_pk_fma_f32 v[36:37], v[132:133], v[4:5], v[36:37]
	v_pk_fma_f32 v[30:31], v[150:151], v[22:23], v[30:31]
	v_pk_fma_f32 v[32:33], v[152:153], v[24:25], v[32:33]
	v_pk_fma_f32 v[34:35], v[138:139], v[10:11], v[34:35]
	v_pk_fma_f32 v[36:37], v[140:141], v[12:13], v[36:37]
	v_mul_f32_e32 v42, 0xbfb8aa3b, v30
	v_mul_f32_e32 v43, 0xbfb8aa3b, v31
	v_mul_f32_e32 v44, 0xbfb8aa3b, v32
	v_mul_f32_e32 v45, 0xbfb8aa3b, v33
	v_exp_f32_e32 v42, v42
	v_exp_f32_e32 v43, v43
	v_exp_f32_e32 v44, v44
	v_exp_f32_e32 v45, v45
	v_pk_add_f32 v[42:43], v[42:43], 1.0 op_sel_hi:[1,0]
	v_pk_add_f32 v[44:45], v[44:45], 1.0 op_sel_hi:[1,0]
	v_rcp_f32_e32 v46, v42
	v_rcp_f32_e32 v47, v43
	v_rcp_f32_e32 v48, v44
	v_rcp_f32_e32 v49, v45
	v_mul_f32_e32 v46, v30, v46
	v_mul_f32_e32 v47, v31, v47
	v_mul_f32_e32 v48, v32, v48
	v_mul_f32_e32 v49, v33, v49
	v_pk_mul_f32 v[34:35], v[34:35], v[46:47]
	v_pk_mul_f32 v[36:37], v[36:37], v[48:49]
	v_cvt_pk_bf16_f32 v66, v34, v35
	v_cvt_pk_bf16_f32 v67, v36, v37
	global_store_dwordx2 v[58:59], v[66:67], off
	v_lshl_add_u64 v[58:59], v[58:59], 0, v[56:57]
	s_waitcnt lgkmcnt(0)
	v_lshlrev_b32_e32 v2, 16, v26
	v_and_b32_e32 v3, 0xffff0000, v26
	v_lshlrev_b32_e32 v4, 16, v27
	v_and_b32_e32 v5, 0xffff0000, v27
	v_lshlrev_b32_e32 v14, 16, v28
	v_and_b32_e32 v15, 0xffff0000, v28
	v_lshlrev_b32_e32 v16, 16, v29
	v_and_b32_e32 v17, 0xffff0000, v29
	v_add_u32_e32 v63, 0x210, v63
	ds_read2_b64 v[26:29], v63 offset1:32
	v_pk_fma_f32 v[30:31], v[146:147], v[22:23], v[158:159]
	v_pk_fma_f32 v[32:33], v[148:149], v[24:25], v[160:161]
	v_pk_fma_f32 v[34:35], v[134:135], v[10:11], v[154:155]
	v_pk_fma_f32 v[36:37], v[136:137], v[12:13], v[156:157]
	v_pk_fma_f32 v[30:31], v[142:143], v[18:19], v[30:31]
	v_pk_fma_f32 v[32:33], v[144:145], v[20:21], v[32:33]
	v_pk_fma_f32 v[34:35], v[130:131], v[6:7], v[34:35]
	v_pk_fma_f32 v[36:37], v[132:133], v[8:9], v[36:37]
	v_pk_fma_f32 v[30:31], v[150:151], v[14:15], v[30:31]
	v_pk_fma_f32 v[32:33], v[152:153], v[16:17], v[32:33]
	v_pk_fma_f32 v[34:35], v[138:139], v[2:3], v[34:35]
	v_pk_fma_f32 v[36:37], v[140:141], v[4:5], v[36:37]
	v_mul_f32_e32 v42, 0xbfb8aa3b, v30
	v_mul_f32_e32 v43, 0xbfb8aa3b, v31
	v_mul_f32_e32 v44, 0xbfb8aa3b, v32
	v_mul_f32_e32 v45, 0xbfb8aa3b, v33
	v_exp_f32_e32 v42, v42
	v_exp_f32_e32 v43, v43
	v_exp_f32_e32 v44, v44
	v_exp_f32_e32 v45, v45
	v_pk_add_f32 v[42:43], v[42:43], 1.0 op_sel_hi:[1,0]
	v_pk_add_f32 v[44:45], v[44:45], 1.0 op_sel_hi:[1,0]
	v_rcp_f32_e32 v46, v42
	v_rcp_f32_e32 v47, v43
	v_rcp_f32_e32 v48, v44
	v_rcp_f32_e32 v49, v45
	v_mul_f32_e32 v46, v30, v46
	v_mul_f32_e32 v47, v31, v47
	v_mul_f32_e32 v48, v32, v48
	v_mul_f32_e32 v49, v33, v49
	v_pk_mul_f32 v[34:35], v[34:35], v[46:47]
	v_pk_mul_f32 v[36:37], v[36:37], v[48:49]
	v_cvt_pk_bf16_f32 v66, v34, v35
	v_cvt_pk_bf16_f32 v67, v36, v37
	global_store_dwordx2 v[58:59], v[66:67], off
	v_lshl_add_u64 v[58:59], v[58:59], 0, v[56:57]
	s_waitcnt lgkmcnt(0)
	v_lshlrev_b32_e32 v6, 16, v26
	v_and_b32_e32 v7, 0xffff0000, v26
	v_lshlrev_b32_e32 v8, 16, v27
	v_and_b32_e32 v9, 0xffff0000, v27
	v_lshlrev_b32_e32 v18, 16, v28
	v_and_b32_e32 v19, 0xffff0000, v28
	v_lshlrev_b32_e32 v20, 16, v29
	v_and_b32_e32 v21, 0xffff0000, v29
	v_add_u32_e32 v63, 0x210, v63
	ds_read2_b64 v[26:29], v63 offset1:32
	v_pk_fma_f32 v[30:31], v[146:147], v[14:15], v[158:159]
	v_pk_fma_f32 v[32:33], v[148:149], v[16:17], v[160:161]
	v_pk_fma_f32 v[34:35], v[134:135], v[2:3], v[154:155]
	v_pk_fma_f32 v[36:37], v[136:137], v[4:5], v[156:157]
	v_pk_fma_f32 v[30:31], v[142:143], v[22:23], v[30:31]
	v_pk_fma_f32 v[32:33], v[144:145], v[24:25], v[32:33]
	v_pk_fma_f32 v[34:35], v[130:131], v[10:11], v[34:35]
	v_pk_fma_f32 v[36:37], v[132:133], v[12:13], v[36:37]
	v_pk_fma_f32 v[30:31], v[150:151], v[18:19], v[30:31]
	v_pk_fma_f32 v[32:33], v[152:153], v[20:21], v[32:33]
	v_pk_fma_f32 v[34:35], v[138:139], v[6:7], v[34:35]
	v_pk_fma_f32 v[36:37], v[140:141], v[8:9], v[36:37]
	v_mul_f32_e32 v42, 0xbfb8aa3b, v30
	v_mul_f32_e32 v43, 0xbfb8aa3b, v31
	v_mul_f32_e32 v44, 0xbfb8aa3b, v32
	v_mul_f32_e32 v45, 0xbfb8aa3b, v33
	v_exp_f32_e32 v42, v42
	v_exp_f32_e32 v43, v43
	v_exp_f32_e32 v44, v44
	v_exp_f32_e32 v45, v45
	v_pk_add_f32 v[42:43], v[42:43], 1.0 op_sel_hi:[1,0]
	v_pk_add_f32 v[44:45], v[44:45], 1.0 op_sel_hi:[1,0]
	v_rcp_f32_e32 v46, v42
	v_rcp_f32_e32 v47, v43
	v_rcp_f32_e32 v48, v44
	v_rcp_f32_e32 v49, v45
	v_mul_f32_e32 v46, v30, v46
	v_mul_f32_e32 v47, v31, v47
	v_mul_f32_e32 v48, v32, v48
	v_mul_f32_e32 v49, v33, v49
	v_pk_mul_f32 v[34:35], v[34:35], v[46:47]
	v_pk_mul_f32 v[36:37], v[36:37], v[48:49]
	v_cvt_pk_bf16_f32 v66, v34, v35
	v_cvt_pk_bf16_f32 v67, v36, v37
	s_and_saveexec_b64 s[4:5], vcc
	global_store_dwordx2 v[58:59], v[66:67], off
	s_or_b64 exec, exec, s[4:5]
	v_lshl_add_u64 v[58:59], v[58:59], 0, v[56:57]
	s_waitcnt lgkmcnt(0)
	v_lshlrev_b32_e32 v10, 16, v26
	v_and_b32_e32 v11, 0xffff0000, v26
	v_lshlrev_b32_e32 v12, 16, v27
	v_and_b32_e32 v13, 0xffff0000, v27
	v_lshlrev_b32_e32 v22, 16, v28
	v_and_b32_e32 v23, 0xffff0000, v28
	v_lshlrev_b32_e32 v24, 16, v29
	v_and_b32_e32 v25, 0xffff0000, v29
	v_pk_fma_f32 v[30:31], v[146:147], v[18:19], v[158:159]
	v_pk_fma_f32 v[32:33], v[148:149], v[20:21], v[160:161]
	v_pk_fma_f32 v[34:35], v[134:135], v[6:7], v[154:155]
	v_pk_fma_f32 v[36:37], v[136:137], v[8:9], v[156:157]
	v_pk_fma_f32 v[30:31], v[142:143], v[14:15], v[30:31]
	v_pk_fma_f32 v[32:33], v[144:145], v[16:17], v[32:33]
	v_pk_fma_f32 v[34:35], v[130:131], v[2:3], v[34:35]
	v_pk_fma_f32 v[36:37], v[132:133], v[4:5], v[36:37]
	v_pk_fma_f32 v[30:31], v[150:151], v[22:23], v[30:31]
	v_pk_fma_f32 v[32:33], v[152:153], v[24:25], v[32:33]
	v_pk_fma_f32 v[34:35], v[138:139], v[10:11], v[34:35]
	v_pk_fma_f32 v[36:37], v[140:141], v[12:13], v[36:37]
	v_mul_f32_e32 v42, 0xbfb8aa3b, v30
	v_mul_f32_e32 v43, 0xbfb8aa3b, v31
	v_mul_f32_e32 v44, 0xbfb8aa3b, v32
	v_mul_f32_e32 v45, 0xbfb8aa3b, v33
	v_exp_f32_e32 v42, v42
	v_exp_f32_e32 v43, v43
	v_exp_f32_e32 v44, v44
	v_exp_f32_e32 v45, v45
	v_pk_add_f32 v[42:43], v[42:43], 1.0 op_sel_hi:[1,0]
	v_pk_add_f32 v[44:45], v[44:45], 1.0 op_sel_hi:[1,0]
	v_rcp_f32_e32 v46, v42
	v_rcp_f32_e32 v47, v43
	v_rcp_f32_e32 v48, v44
	v_rcp_f32_e32 v49, v45
	v_mul_f32_e32 v46, v30, v46
	v_mul_f32_e32 v47, v31, v47
	v_mul_f32_e32 v48, v32, v48
	v_mul_f32_e32 v49, v33, v49
	v_pk_mul_f32 v[34:35], v[34:35], v[46:47]
	v_pk_mul_f32 v[36:37], v[36:37], v[48:49]
	v_cvt_pk_bf16_f32 v66, v34, v35
	v_cvt_pk_bf16_f32 v67, v36, v37
	s_and_saveexec_b64 s[4:5], vcc
	global_store_dwordx2 v[58:59], v[66:67], off
	s_or_b64 exec, exec, s[4:5]
	v_lshl_add_u64 v[58:59], v[58:59], 0, v[56:57]
	s_branch .Lconv_done
